# WQ absorbed-weight prep remapped to 8x8 lanes for coalesced loads (phase-1 tail)
# speedup vs baseline: 1.0001x; 1.0001x over previous
; #define GAS __attribute__((address_space(1)))
; #define P (*args_here())
; DI void p0_small(const Ptrs& P, int gt, int NGT) {
;     ...
;     { bf16* WQ = (bf16*)(ws + WS_WQ); const float* uq = P.in[14]; const float* uk = P.in[16];
;       for (int i = gt; i < 8 * 32 * 64; i += NGT) { const int cq = i & 63, rq = (i >> 6) & 31, hd = i >> 11;
;           const float* a = uq + (size_t)(4 * cq) * 768 + hd * 96; const float* b = uk + (size_t)(4 * rq) * 512 + hd * 64;
;           f32x4 acc[4];
; #pragma unroll
;           for (int rr = 0; rr < 4; ++rr) acc[rr] = (f32x4){0.f, 0.f, 0.f, 0.f};
; #pragma unroll 4
;           for (int j4 = 0; j4 < 16; ++j4) { f32x4 av[4], bv[4];
; #pragma unroll
;               for (int t = 0; t < 4; ++t) { av[t] = *(const GAS f32x4*)(a + t * 768 + 4 * j4); bv[t] = *(const GAS f32x4*)(b + t * 512 + 4 * j4); }
.LBB0_128:
	s_or_b64 exec, exec, s[6:7]
	s_load_dwordx2 s[8:9], s[2:3], 0x70
	s_waitcnt lgkmcnt(0)
	s_add_u32 s6, s4, 0x2900000
	s_movk_i32 s0, 0x4000
	s_addc_u32 s7, s5, 0
	v_cmp_gt_u32_e32 vcc, s0, v106
	v_lshlrev_b32_e32 v132, 2, v106
	s_and_saveexec_b64 s[10:11], vcc
	s_cbranch_execz .LBB0_132
	s_load_dwordx2 s[0:1], s[2:3], 0x80
	v_lshrrev_b32_e32 v107, 11, v106
	v_lshrrev_b32_e32 v2, 1, v106
	v_and_b32_e32 v134, 28, v132
	v_and_b32_e32 v3, 0xe0, v2
	v_or_b32_e32 v134, v134, v3
	v_and_b32_e32 v133, 28, v2
	v_lshrrev_b32_e32 v2, 4, v106
	v_and_b32_e32 v2, 0x60, v2
	v_or_b32_e32 v133, v133, v2
	v_mul_u32_u24_e32 v4, 0x60, v107
	s_movk_i32 s12, 0xc00
	v_mov_b64_e32 v[2:3], s[8:9]
	v_mad_u64_u32 v[2:3], s[12:13], v134, s12, v[2:3]
	v_lshlrev_b32_e32 v112, 2, v4
	v_mov_b32_e32 v113, 0
	v_lshl_add_u64 v[108:109], v[2:3], 0, v[112:113]
	v_lshlrev_b32_e32 v112, 11, v133
	s_waitcnt lgkmcnt(0)
	v_lshl_add_u64 v[2:3], s[0:1], 0, v[112:113]
	v_lshlrev_b32_e32 v112, 8, v107
	v_lshl_add_u64 v[110:111], v[2:3], 0, v[112:113]
	s_mov_b64 s[12:13], 0
	s_mov_b64 s[14:15], 0x1800
	s_movk_i32 s0, 0x1000
	s_mov_b64 s[16:17], 0x1000
	s_mov_b64 s[18:19], 0x2400
	s_movk_i32 s1, 0x2000
	v_mov_b32_e32 v112, v113
	v_mov_b32_e32 v114, v113
	v_mov_b32_e32 v115, v113
	v_mov_b32_e32 v118, v113
	v_mov_b32_e32 v119, v113
	v_mov_b32_e32 v116, v113
	v_mov_b32_e32 v117, v113
	v_mov_b32_e32 v122, v113
	v_mov_b32_e32 v123, v113
	v_mov_b32_e32 v120, v113
	v_mov_b32_e32 v121, v113
	v_mov_b32_e32 v124, v113
	v_mov_b32_e32 v125, v113
	v_mov_b32_e32 v126, v113
	v_mov_b32_e32 v127, v113
